# barrier-nonleaders-poll-TOPGEN
# baseline (speedup 1.0000x reference)
.LBB0_40:
	s_lshl_b32 s3, s65, 8
	s_add_u32 s8, s70, s3
	s_addc_u32 s9, s71, 0
	v_mov_b32_e32 v2, 0x1000
	v_mov_b32_e32 v4, 1
	global_atomic_add v4, v2, v4, s[8:9] offset:1024 sc0
	v_cvt_f32_u32_e32 v2, v3
	v_sub_u32_e32 v5, 0, v3
	v_rcp_iflag_f32_e32 v2, v2
	s_nop 0
	v_mul_f32_e32 v2, 0x4f7ffffe, v2
	v_cvt_u32_f32_e32 v2, v2
	v_mul_lo_u32 v5, v5, v2
	v_mul_hi_u32 v5, v2, v5
	v_add_u32_e32 v2, v2, v5
	s_waitcnt vmcnt(0)
	v_mul_hi_u32 v2, v4, v2
	v_mul_lo_u32 v5, v2, v3
	v_sub_u32_e32 v5, v4, v5
	v_add_u32_e32 v6, 1, v2
	v_cmp_ge_u32_e32 vcc, v5, v3
	v_add_u32_e32 v4, 1, v4
	s_nop 0
	v_cndmask_b32_e32 v2, v2, v6, vcc
	v_sub_u32_e32 v6, v5, v3
	v_cndmask_b32_e32 v5, v5, v6, vcc
	v_add_u32_e32 v6, 1, v2
	v_cmp_ge_u32_e32 vcc, v5, v3
	s_nop 1
	v_cndmask_b32_e32 v2, v2, v6, vcc
	v_mul_lo_u32 v5, v3, v2
	v_add_u32_e32 v3, v5, v3
	v_cmp_ne_u32_e32 vcc, v4, v3
	s_and_saveexec_b64 s[10:11], vcc
	s_xor_b64 s[10:11], exec, s[10:11]
	s_cbranch_execz .LBB0_54
	s_waitcnt lgkmcnt(0)
	v_mov_b32_e32 v1, 0x3500
	global_load_dword v1, v1, s[70:71] sc1
	s_add_u32 s14, s70, 0x3500
	s_addc_u32 s15, s71, 0
	v_mov_b32_e32 v2, 0
	s_waitcnt vmcnt(0)
	v_cmp_eq_u32_e32 vcc, v1, v2
	s_and_saveexec_b64 s[12:13], vcc
	s_cbranch_execz .LBB0_53
	s_mov_b32 s3, 1
	s_mov_b64 s[16:17], 0
	v_mov_b32_e32 v1, 0
	s_branch .LBB0_44

.LBB0_194:
	s_lshl_b32 s3, s65, 8
	s_add_u32 s6, s70, s3
	s_addc_u32 s7, s71, 0
	v_mov_b32_e32 v2, 0x1000
	v_mov_b32_e32 v4, 1
	global_atomic_add v4, v2, v4, s[6:7] offset:1024 sc0
	v_cvt_f32_u32_e32 v2, v3
	v_sub_u32_e32 v5, 0, v3
	v_rcp_iflag_f32_e32 v2, v2
	s_nop 0
	v_mul_f32_e32 v2, 0x4f7ffffe, v2
	v_cvt_u32_f32_e32 v2, v2
	v_mul_lo_u32 v5, v5, v2
	v_mul_hi_u32 v5, v2, v5
	v_add_u32_e32 v2, v2, v5
	s_waitcnt vmcnt(0)
	v_mul_hi_u32 v2, v4, v2
	v_mul_lo_u32 v5, v2, v3
	v_sub_u32_e32 v5, v4, v5
	v_add_u32_e32 v6, 1, v2
	v_cmp_ge_u32_e32 vcc, v5, v3
	v_add_u32_e32 v4, 1, v4
	s_nop 0
	v_cndmask_b32_e32 v2, v2, v6, vcc
	v_sub_u32_e32 v6, v5, v3
	v_cndmask_b32_e32 v5, v5, v6, vcc
	v_add_u32_e32 v6, 1, v2
	v_cmp_ge_u32_e32 vcc, v5, v3
	s_nop 1
	v_cndmask_b32_e32 v2, v2, v6, vcc
	v_mul_lo_u32 v5, v3, v2
	v_add_u32_e32 v3, v5, v3
	v_cmp_ne_u32_e32 vcc, v4, v3
	s_and_saveexec_b64 s[8:9], vcc
	s_xor_b64 s[8:9], exec, s[8:9]
	s_cbranch_execz .LBB0_208
	s_waitcnt lgkmcnt(0)
	v_mov_b32_e32 v1, 0x3500
	global_load_dword v1, v1, s[70:71] sc1
	s_add_u32 s12, s70, 0x3500
	s_addc_u32 s13, s71, 0
	v_mov_b32_e32 v2, 1
	s_waitcnt vmcnt(0)
	v_cmp_eq_u32_e32 vcc, v1, v2
	s_and_saveexec_b64 s[10:11], vcc
	s_cbranch_execz .LBB0_207
	s_mov_b32 s3, 1
	s_mov_b64 s[22:23], 0
	v_mov_b32_e32 v1, 0
	s_branch .LBB0_198

.LBB0_268:
	s_lshl_b32 s3, s65, 8
	s_add_u32 s6, s70, s3
	s_addc_u32 s7, s71, 0
	v_mov_b32_e32 v2, 0x1000
	v_mov_b32_e32 v4, 1
	global_atomic_add v4, v2, v4, s[6:7] offset:1024 sc0
	v_cvt_f32_u32_e32 v2, v3
	v_sub_u32_e32 v5, 0, v3
	v_rcp_iflag_f32_e32 v2, v2
	s_nop 0
	v_mul_f32_e32 v2, 0x4f7ffffe, v2
	v_cvt_u32_f32_e32 v2, v2
	v_mul_lo_u32 v5, v5, v2
	v_mul_hi_u32 v5, v2, v5
	v_add_u32_e32 v2, v2, v5
	s_waitcnt vmcnt(0)
	v_mul_hi_u32 v2, v4, v2
	v_mul_lo_u32 v5, v2, v3
	v_sub_u32_e32 v5, v4, v5
	v_add_u32_e32 v6, 1, v2
	v_cmp_ge_u32_e32 vcc, v5, v3
	v_add_u32_e32 v4, 1, v4
	s_nop 0
	v_cndmask_b32_e32 v2, v2, v6, vcc
	v_sub_u32_e32 v6, v5, v3
	v_cndmask_b32_e32 v5, v5, v6, vcc
	v_add_u32_e32 v6, 1, v2
	v_cmp_ge_u32_e32 vcc, v5, v3
	s_nop 1
	v_cndmask_b32_e32 v2, v2, v6, vcc
	v_mul_lo_u32 v5, v3, v2
	v_add_u32_e32 v3, v5, v3
	v_cmp_ne_u32_e32 vcc, v4, v3
	s_and_saveexec_b64 s[8:9], vcc
	s_xor_b64 s[8:9], exec, s[8:9]
	s_cbranch_execz .LBB0_282
	s_waitcnt lgkmcnt(0)
	v_mov_b32_e32 v1, 0x3500
	global_load_dword v1, v1, s[70:71] sc1
	s_add_u32 s12, s70, 0x3500
	s_addc_u32 s13, s71, 0
	v_mov_b32_e32 v2, 2
	s_waitcnt vmcnt(0)
	v_cmp_eq_u32_e32 vcc, v1, v2
	s_and_saveexec_b64 s[10:11], vcc
	s_cbranch_execz .LBB0_281
	s_mov_b32 s3, 1
	s_mov_b64 s[22:23], 0
	v_mov_b32_e32 v1, 0
	s_branch .LBB0_272

.LBB0_379:
	s_lshl_b32 s3, s65, 8
	s_add_u32 s8, s70, s3
	s_addc_u32 s9, s71, 0
	v_mov_b32_e32 v2, 0x1000
	v_mov_b32_e32 v4, 1
	global_atomic_add v4, v2, v4, s[8:9] offset:1024 sc0
	v_cvt_f32_u32_e32 v2, v3
	v_sub_u32_e32 v5, 0, v3
	v_rcp_iflag_f32_e32 v2, v2
	s_nop 0
	v_mul_f32_e32 v2, 0x4f7ffffe, v2
	v_cvt_u32_f32_e32 v2, v2
	v_mul_lo_u32 v5, v5, v2
	v_mul_hi_u32 v5, v2, v5
	v_add_u32_e32 v2, v2, v5
	s_waitcnt vmcnt(0)
	v_mul_hi_u32 v2, v4, v2
	v_mul_lo_u32 v5, v2, v3
	v_sub_u32_e32 v5, v4, v5
	v_add_u32_e32 v6, 1, v2
	v_cmp_ge_u32_e32 vcc, v5, v3
	v_add_u32_e32 v4, 1, v4
	s_nop 0
	v_cndmask_b32_e32 v2, v2, v6, vcc
	v_sub_u32_e32 v6, v5, v3
	v_cndmask_b32_e32 v5, v5, v6, vcc
	v_add_u32_e32 v6, 1, v2
	v_cmp_ge_u32_e32 vcc, v5, v3
	s_nop 1
	v_cndmask_b32_e32 v2, v2, v6, vcc
	v_mul_lo_u32 v5, v3, v2
	v_add_u32_e32 v3, v5, v3
	v_cmp_ne_u32_e32 vcc, v4, v3
	s_and_saveexec_b64 s[10:11], vcc
	s_xor_b64 s[10:11], exec, s[10:11]
	s_cbranch_execz .LBB0_393
	s_waitcnt lgkmcnt(0)
	v_mov_b32_e32 v1, 0x3500
	global_load_dword v1, v1, s[70:71] sc1
	s_add_u32 s22, s70, 0x3500
	s_addc_u32 s23, s71, 0
	v_mov_b32_e32 v2, 3
	s_waitcnt vmcnt(0)
	v_cmp_eq_u32_e32 vcc, v1, v2
	s_and_saveexec_b64 s[12:13], vcc
	s_cbranch_execz .LBB0_392
	s_mov_b32 s3, 1
	s_mov_b64 s[24:25], 0
	v_mov_b32_e32 v1, 0
	s_branch .LBB0_383

.LBB0_482:
	s_lshl_b32 s3, s65, 8
	s_add_u32 s8, s70, s3
	s_addc_u32 s9, s71, 0
	v_mov_b32_e32 v2, 0x1000
	v_mov_b32_e32 v4, 1
	global_atomic_add v4, v2, v4, s[8:9] offset:1024 sc0
	v_cvt_f32_u32_e32 v2, v3
	v_sub_u32_e32 v5, 0, v3
	v_rcp_iflag_f32_e32 v2, v2
	s_nop 0
	v_mul_f32_e32 v2, 0x4f7ffffe, v2
	v_cvt_u32_f32_e32 v2, v2
	v_mul_lo_u32 v5, v5, v2
	v_mul_hi_u32 v5, v2, v5
	v_add_u32_e32 v2, v2, v5
	s_waitcnt vmcnt(0)
	v_mul_hi_u32 v2, v4, v2
	v_mul_lo_u32 v5, v2, v3
	v_sub_u32_e32 v5, v4, v5
	v_add_u32_e32 v6, 1, v2
	v_cmp_ge_u32_e32 vcc, v5, v3
	v_add_u32_e32 v4, 1, v4
	s_nop 0
	v_cndmask_b32_e32 v2, v2, v6, vcc
	v_sub_u32_e32 v6, v5, v3
	v_cndmask_b32_e32 v5, v5, v6, vcc
	v_add_u32_e32 v6, 1, v2
	v_cmp_ge_u32_e32 vcc, v5, v3
	s_nop 1
	v_cndmask_b32_e32 v2, v2, v6, vcc
	v_mul_lo_u32 v5, v3, v2
	v_add_u32_e32 v3, v5, v3
	v_cmp_ne_u32_e32 vcc, v4, v3
	s_and_saveexec_b64 s[10:11], vcc
	s_xor_b64 s[10:11], exec, s[10:11]
	s_cbranch_execz .LBB0_496
	s_waitcnt lgkmcnt(0)
	v_mov_b32_e32 v1, 0x3500
	global_load_dword v1, v1, s[70:71] sc1
	s_add_u32 s20, s70, 0x3500
	s_addc_u32 s21, s71, 0
	v_mov_b32_e32 v2, 4
	s_waitcnt vmcnt(0)
	v_cmp_eq_u32_e32 vcc, v1, v2
	s_and_saveexec_b64 s[12:13], vcc
	s_cbranch_execz .LBB0_495
	s_mov_b32 s3, 1
	s_mov_b64 s[22:23], 0
	v_mov_b32_e32 v1, 0
	s_branch .LBB0_486

.LBB0_559:
	s_lshl_b32 s3, s65, 8
	s_add_u32 s8, s70, s3
	s_addc_u32 s9, s71, 0
	v_mov_b32_e32 v2, 0x1000
	v_mov_b32_e32 v4, 1
	global_atomic_add v4, v2, v4, s[8:9] offset:1024 sc0
	v_cvt_f32_u32_e32 v2, v3
	v_sub_u32_e32 v5, 0, v3
	v_rcp_iflag_f32_e32 v2, v2
	s_nop 0
	v_mul_f32_e32 v2, 0x4f7ffffe, v2
	v_cvt_u32_f32_e32 v2, v2
	v_mul_lo_u32 v5, v5, v2
	v_mul_hi_u32 v5, v2, v5
	v_add_u32_e32 v2, v2, v5
	s_waitcnt vmcnt(0)
	v_mul_hi_u32 v2, v4, v2
	v_mul_lo_u32 v5, v2, v3
	v_sub_u32_e32 v5, v4, v5
	v_add_u32_e32 v6, 1, v2
	v_cmp_ge_u32_e32 vcc, v5, v3
	v_add_u32_e32 v4, 1, v4
	s_nop 0
	v_cndmask_b32_e32 v2, v2, v6, vcc
	v_sub_u32_e32 v6, v5, v3
	v_cndmask_b32_e32 v5, v5, v6, vcc
	v_add_u32_e32 v6, 1, v2
	v_cmp_ge_u32_e32 vcc, v5, v3
	s_nop 1
	v_cndmask_b32_e32 v2, v2, v6, vcc
	v_mul_lo_u32 v5, v3, v2
	v_add_u32_e32 v3, v5, v3
	v_cmp_ne_u32_e32 vcc, v4, v3
	s_and_saveexec_b64 s[10:11], vcc
	s_xor_b64 s[10:11], exec, s[10:11]
	s_cbranch_execz .LBB0_573
	s_waitcnt lgkmcnt(0)
	v_mov_b32_e32 v1, 0x3500
	global_load_dword v1, v1, s[70:71] sc1
	s_add_u32 s20, s70, 0x3500
	s_addc_u32 s21, s71, 0
	v_mov_b32_e32 v2, 5
	s_waitcnt vmcnt(0)
	v_cmp_eq_u32_e32 vcc, v1, v2
	s_and_saveexec_b64 s[12:13], vcc
	s_cbranch_execz .LBB0_572
	s_mov_b32 s3, 1
	s_mov_b64 s[22:23], 0
	v_mov_b32_e32 v1, 0
	s_branch .LBB0_563

.LBB0_640:
	s_lshl_b32 s3, s65, 8
	s_add_u32 s6, s70, s3
	s_addc_u32 s7, s71, 0
	v_mov_b32_e32 v2, 0x1000
	v_mov_b32_e32 v4, 1
	global_atomic_add v4, v2, v4, s[6:7] offset:1024 sc0
	v_cvt_f32_u32_e32 v2, v3
	v_sub_u32_e32 v5, 0, v3
	v_rcp_iflag_f32_e32 v2, v2
	s_nop 0
	v_mul_f32_e32 v2, 0x4f7ffffe, v2
	v_cvt_u32_f32_e32 v2, v2
	v_mul_lo_u32 v5, v5, v2
	v_mul_hi_u32 v5, v2, v5
	v_add_u32_e32 v2, v2, v5
	s_waitcnt vmcnt(0)
	v_mul_hi_u32 v2, v4, v2
	v_mul_lo_u32 v5, v2, v3
	v_sub_u32_e32 v5, v4, v5
	v_add_u32_e32 v6, 1, v2
	v_cmp_ge_u32_e32 vcc, v5, v3
	v_add_u32_e32 v4, 1, v4
	s_nop 0
	v_cndmask_b32_e32 v2, v2, v6, vcc
	v_sub_u32_e32 v6, v5, v3
	v_cndmask_b32_e32 v5, v5, v6, vcc
	v_add_u32_e32 v6, 1, v2
	v_cmp_ge_u32_e32 vcc, v5, v3
	s_nop 1
	v_cndmask_b32_e32 v2, v2, v6, vcc
	v_mul_lo_u32 v5, v3, v2
	v_add_u32_e32 v3, v5, v3
	v_cmp_ne_u32_e32 vcc, v4, v3
	s_and_saveexec_b64 s[8:9], vcc
	s_xor_b64 s[8:9], exec, s[8:9]
	s_cbranch_execz .LBB0_654
	s_waitcnt lgkmcnt(0)
	v_mov_b32_e32 v1, 0x3500
	global_load_dword v1, v1, s[70:71] sc1
	s_add_u32 s12, s70, 0x3500
	s_addc_u32 s13, s71, 0
	v_mov_b32_e32 v2, 6
	s_waitcnt vmcnt(0)
	v_cmp_eq_u32_e32 vcc, v1, v2
	s_and_saveexec_b64 s[10:11], vcc
	s_cbranch_execz .LBB0_653
	s_mov_b32 s3, 1
	s_mov_b64 s[20:21], 0
	v_mov_b32_e32 v1, 0
	s_branch .LBB0_644

.LBB0_743:
	s_lshl_b32 s3, s65, 8
	s_add_u32 s6, s70, s3
	s_addc_u32 s7, s71, 0
	v_mov_b32_e32 v2, 0x1000
	v_mov_b32_e32 v4, 1
	global_atomic_add v4, v2, v4, s[6:7] offset:1024 sc0
	v_cvt_f32_u32_e32 v2, v3
	v_sub_u32_e32 v5, 0, v3
	v_rcp_iflag_f32_e32 v2, v2
	s_nop 0
	v_mul_f32_e32 v2, 0x4f7ffffe, v2
	v_cvt_u32_f32_e32 v2, v2
	v_mul_lo_u32 v5, v5, v2
	v_mul_hi_u32 v5, v2, v5
	v_add_u32_e32 v2, v2, v5
	s_waitcnt vmcnt(0)
	v_mul_hi_u32 v2, v4, v2
	v_mul_lo_u32 v5, v2, v3
	v_sub_u32_e32 v5, v4, v5
	v_add_u32_e32 v6, 1, v2
	v_cmp_ge_u32_e32 vcc, v5, v3
	v_add_u32_e32 v4, 1, v4
	s_nop 0
	v_cndmask_b32_e32 v2, v2, v6, vcc
	v_sub_u32_e32 v6, v5, v3
	v_cndmask_b32_e32 v5, v5, v6, vcc
	v_add_u32_e32 v6, 1, v2
	v_cmp_ge_u32_e32 vcc, v5, v3
	s_nop 1
	v_cndmask_b32_e32 v2, v2, v6, vcc
	v_mul_lo_u32 v5, v3, v2
	v_add_u32_e32 v3, v5, v3
	v_cmp_ne_u32_e32 vcc, v4, v3
	s_and_saveexec_b64 s[8:9], vcc
	s_xor_b64 s[8:9], exec, s[8:9]
	s_cbranch_execz .LBB0_757
	s_waitcnt lgkmcnt(0)
	v_mov_b32_e32 v1, 0x3500
	global_load_dword v1, v1, s[70:71] sc1
	s_add_u32 s12, s70, 0x3500
	s_addc_u32 s13, s71, 0
	v_mov_b32_e32 v2, 7
	s_waitcnt vmcnt(0)
	v_cmp_eq_u32_e32 vcc, v1, v2
	s_and_saveexec_b64 s[10:11], vcc
	s_cbranch_execz .LBB0_756
	s_mov_b32 s3, 1
	s_mov_b64 s[18:19], 0
	v_mov_b32_e32 v1, 0
	s_branch .LBB0_747

.LBB0_814:
	s_lshl_b32 s3, s65, 8
	s_add_u32 s6, s70, s3
	s_addc_u32 s7, s71, 0
	v_mov_b32_e32 v2, 0x1000
	v_mov_b32_e32 v4, 1
	global_atomic_add v4, v2, v4, s[6:7] offset:1024 sc0
	v_cvt_f32_u32_e32 v2, v3
	v_sub_u32_e32 v5, 0, v3
	v_rcp_iflag_f32_e32 v2, v2
	s_nop 0
	v_mul_f32_e32 v2, 0x4f7ffffe, v2
	v_cvt_u32_f32_e32 v2, v2
	v_mul_lo_u32 v5, v5, v2
	v_mul_hi_u32 v5, v2, v5
	v_add_u32_e32 v2, v2, v5
	s_waitcnt vmcnt(0)
	v_mul_hi_u32 v2, v4, v2
	v_mul_lo_u32 v5, v2, v3
	v_sub_u32_e32 v5, v4, v5
	v_add_u32_e32 v6, 1, v2
	v_cmp_ge_u32_e32 vcc, v5, v3
	v_add_u32_e32 v4, 1, v4
	s_nop 0
	v_cndmask_b32_e32 v2, v2, v6, vcc
	v_sub_u32_e32 v6, v5, v3
	v_cndmask_b32_e32 v5, v5, v6, vcc
	v_add_u32_e32 v6, 1, v2
	v_cmp_ge_u32_e32 vcc, v5, v3
	s_nop 1
	v_cndmask_b32_e32 v2, v2, v6, vcc
	v_mul_lo_u32 v5, v3, v2
	v_add_u32_e32 v3, v5, v3
	v_cmp_ne_u32_e32 vcc, v4, v3
	s_and_saveexec_b64 s[8:9], vcc
	s_xor_b64 s[8:9], exec, s[8:9]
	s_cbranch_execz .LBB0_828
	s_waitcnt lgkmcnt(0)
	v_mov_b32_e32 v1, 0x3500
	global_load_dword v1, v1, s[70:71] sc1
	s_add_u32 s12, s70, 0x3500
	s_addc_u32 s13, s71, 0
	v_mov_b32_e32 v2, 8
	s_waitcnt vmcnt(0)
	v_cmp_eq_u32_e32 vcc, v1, v2
	s_and_saveexec_b64 s[10:11], vcc
	s_cbranch_execz .LBB0_827
	s_mov_b32 s3, 1
	s_mov_b64 s[18:19], 0
	v_mov_b32_e32 v1, 0
	s_branch .LBB0_818

.LBB0_1064:
	s_lshl_b32 s3, s65, 8
	s_add_u32 s6, s70, s3
	s_addc_u32 s7, s71, 0
	v_mov_b32_e32 v2, 0x1000
	v_mov_b32_e32 v4, 1
	global_atomic_add v4, v2, v4, s[6:7] offset:1024 sc0
	v_cvt_f32_u32_e32 v2, v3
	v_sub_u32_e32 v5, 0, v3
	v_rcp_iflag_f32_e32 v2, v2
	s_nop 0
	v_mul_f32_e32 v2, 0x4f7ffffe, v2
	v_cvt_u32_f32_e32 v2, v2
	v_mul_lo_u32 v5, v5, v2
	v_mul_hi_u32 v5, v2, v5
	v_add_u32_e32 v2, v2, v5
	s_waitcnt vmcnt(0)
	v_mul_hi_u32 v2, v4, v2
	v_mul_lo_u32 v5, v2, v3
	v_sub_u32_e32 v5, v4, v5
	v_add_u32_e32 v6, 1, v2
	v_cmp_ge_u32_e32 vcc, v5, v3
	v_add_u32_e32 v4, 1, v4
	s_nop 0
	v_cndmask_b32_e32 v2, v2, v6, vcc
	v_sub_u32_e32 v6, v5, v3
	v_cndmask_b32_e32 v5, v5, v6, vcc
	v_add_u32_e32 v6, 1, v2
	v_cmp_ge_u32_e32 vcc, v5, v3
	s_nop 1
	v_cndmask_b32_e32 v2, v2, v6, vcc
	v_mul_lo_u32 v5, v3, v2
	v_add_u32_e32 v3, v5, v3
	v_cmp_ne_u32_e32 vcc, v4, v3
	s_and_saveexec_b64 s[8:9], vcc
	s_xor_b64 s[8:9], exec, s[8:9]
	s_cbranch_execz .LBB0_1078
	s_waitcnt lgkmcnt(0)
	v_mov_b32_e32 v1, 0x3500
	global_load_dword v1, v1, s[70:71] sc1
	s_add_u32 s12, s70, 0x3500
	s_addc_u32 s13, s71, 0
	v_mov_b32_e32 v2, 9
	s_waitcnt vmcnt(0)
	v_cmp_eq_u32_e32 vcc, v1, v2
	s_and_saveexec_b64 s[10:11], vcc
	s_cbranch_execz .LBB0_1077
	s_mov_b32 s3, 1
	s_mov_b64 s[14:15], 0
	v_mov_b32_e32 v1, 0
	s_branch .LBB0_1068

.LBB0_1197:
	s_lshl_b32 s3, s65, 8
	s_add_u32 s6, s70, s3
	s_addc_u32 s7, s71, 0
	v_mov_b32_e32 v2, 0x1000
	v_mov_b32_e32 v4, 1
	global_atomic_add v4, v2, v4, s[6:7] offset:1024 sc0
	v_cvt_f32_u32_e32 v2, v3
	v_sub_u32_e32 v5, 0, v3
	v_rcp_iflag_f32_e32 v2, v2
	s_nop 0
	v_mul_f32_e32 v2, 0x4f7ffffe, v2
	v_cvt_u32_f32_e32 v2, v2
	v_mul_lo_u32 v5, v5, v2
	v_mul_hi_u32 v5, v2, v5
	v_add_u32_e32 v2, v2, v5
	s_waitcnt vmcnt(0)
	v_mul_hi_u32 v2, v4, v2
	v_mul_lo_u32 v5, v2, v3
	v_sub_u32_e32 v5, v4, v5
	v_add_u32_e32 v6, 1, v2
	v_cmp_ge_u32_e32 vcc, v5, v3
	v_add_u32_e32 v4, 1, v4
	s_nop 0
	v_cndmask_b32_e32 v2, v2, v6, vcc
	v_sub_u32_e32 v6, v5, v3
	v_cndmask_b32_e32 v5, v5, v6, vcc
	v_add_u32_e32 v6, 1, v2
	v_cmp_ge_u32_e32 vcc, v5, v3
	s_nop 1
	v_cndmask_b32_e32 v2, v2, v6, vcc
	v_mul_lo_u32 v5, v3, v2
	v_add_u32_e32 v3, v5, v3
	v_cmp_ne_u32_e32 vcc, v4, v3
	s_and_saveexec_b64 s[8:9], vcc
	s_xor_b64 s[8:9], exec, s[8:9]
	s_cbranch_execz .LBB0_1211
	s_waitcnt lgkmcnt(0)
	v_mov_b32_e32 v1, 0x3500
	global_load_dword v1, v1, s[70:71] sc1
	s_add_u32 s12, s70, 0x3500
	s_addc_u32 s13, s71, 0
	v_mov_b32_e32 v2, 10
	s_waitcnt vmcnt(0)
	v_cmp_eq_u32_e32 vcc, v1, v2
	s_and_saveexec_b64 s[10:11], vcc
	s_cbranch_execz .LBB0_1210
	s_mov_b32 s3, 1
	s_mov_b64 s[14:15], 0
	v_mov_b32_e32 v1, 0
	s_branch .LBB0_1201

.LBB0_1300:
	s_lshl_b32 s3, s65, 8
	s_add_u32 s6, s70, s3
	s_addc_u32 s7, s71, 0
	v_mov_b32_e32 v2, 0x1000
	v_mov_b32_e32 v4, 1
	global_atomic_add v4, v2, v4, s[6:7] offset:1024 sc0
	v_cvt_f32_u32_e32 v2, v3
	v_sub_u32_e32 v5, 0, v3
	v_rcp_iflag_f32_e32 v2, v2
	s_nop 0
	v_mul_f32_e32 v2, 0x4f7ffffe, v2
	v_cvt_u32_f32_e32 v2, v2
	v_mul_lo_u32 v5, v5, v2
	v_mul_hi_u32 v5, v2, v5
	v_add_u32_e32 v2, v2, v5
	s_waitcnt vmcnt(0)
	v_mul_hi_u32 v2, v4, v2
	v_mul_lo_u32 v5, v2, v3
	v_sub_u32_e32 v5, v4, v5
	v_add_u32_e32 v6, 1, v2
	v_cmp_ge_u32_e32 vcc, v5, v3
	v_add_u32_e32 v4, 1, v4
	s_nop 0
	v_cndmask_b32_e32 v2, v2, v6, vcc
	v_sub_u32_e32 v6, v5, v3
	v_cndmask_b32_e32 v5, v5, v6, vcc
	v_add_u32_e32 v6, 1, v2
	v_cmp_ge_u32_e32 vcc, v5, v3
	s_nop 1
	v_cndmask_b32_e32 v2, v2, v6, vcc
	v_mul_lo_u32 v5, v3, v2
	v_add_u32_e32 v3, v5, v3
	v_cmp_ne_u32_e32 vcc, v4, v3
	s_and_saveexec_b64 s[8:9], vcc
	s_xor_b64 s[8:9], exec, s[8:9]
	s_cbranch_execz .LBB0_1314
	s_waitcnt lgkmcnt(0)
	v_mov_b32_e32 v1, 0x3500
	global_load_dword v1, v1, s[70:71] sc1
	s_add_u32 s12, s70, 0x3500
	s_addc_u32 s13, s71, 0
	v_mov_b32_e32 v2, 11
	s_waitcnt vmcnt(0)
	v_cmp_eq_u32_e32 vcc, v1, v2
	s_and_saveexec_b64 s[10:11], vcc
	s_cbranch_execz .LBB0_1313
	s_mov_b32 s3, 1
	s_mov_b64 s[14:15], 0
	v_mov_b32_e32 v1, 0
	s_branch .LBB0_1304

.LBB0_1371:
	s_lshl_b32 s3, s65, 8
	s_add_u32 s6, s70, s3
	s_addc_u32 s7, s71, 0
	v_mov_b32_e32 v2, 0x1000
	v_mov_b32_e32 v4, 1
	global_atomic_add v4, v2, v4, s[6:7] offset:1024 sc0
	v_cvt_f32_u32_e32 v2, v3
	v_sub_u32_e32 v5, 0, v3
	v_rcp_iflag_f32_e32 v2, v2
	s_nop 0
	v_mul_f32_e32 v2, 0x4f7ffffe, v2
	v_cvt_u32_f32_e32 v2, v2
	v_mul_lo_u32 v5, v5, v2
	v_mul_hi_u32 v5, v2, v5
	v_add_u32_e32 v2, v2, v5
	s_waitcnt vmcnt(0)
	v_mul_hi_u32 v2, v4, v2
	v_mul_lo_u32 v5, v2, v3
	v_sub_u32_e32 v5, v4, v5
	v_add_u32_e32 v6, 1, v2
	v_cmp_ge_u32_e32 vcc, v5, v3
	v_add_u32_e32 v4, 1, v4
	s_nop 0
	v_cndmask_b32_e32 v2, v2, v6, vcc
	v_sub_u32_e32 v6, v5, v3
	v_cndmask_b32_e32 v5, v5, v6, vcc
	v_add_u32_e32 v6, 1, v2
	v_cmp_ge_u32_e32 vcc, v5, v3
	s_nop 1
	v_cndmask_b32_e32 v2, v2, v6, vcc
	v_mul_lo_u32 v5, v3, v2
	v_add_u32_e32 v3, v5, v3
	v_cmp_ne_u32_e32 vcc, v4, v3
	s_and_saveexec_b64 s[8:9], vcc
	s_xor_b64 s[8:9], exec, s[8:9]
	s_cbranch_execz .LBB0_1385
	s_waitcnt lgkmcnt(0)
	v_mov_b32_e32 v1, 0x3500
	global_load_dword v1, v1, s[70:71] sc1
	s_add_u32 s12, s70, 0x3500
	s_addc_u32 s13, s71, 0
	v_mov_b32_e32 v2, 12
	s_waitcnt vmcnt(0)
	v_cmp_eq_u32_e32 vcc, v1, v2
	s_and_saveexec_b64 s[10:11], vcc
	s_cbranch_execz .LBB0_1384
	s_mov_b32 s3, 1
	s_mov_b64 s[14:15], 0
	v_mov_b32_e32 v1, 0
	s_branch .LBB0_1375

.LBB0_1452:
	s_lshl_b32 s3, s65, 8
	s_add_u32 s6, s70, s3
	s_addc_u32 s7, s71, 0
	v_mov_b32_e32 v2, 0x1000
	v_mov_b32_e32 v4, 1
	global_atomic_add v4, v2, v4, s[6:7] offset:1024 sc0
	v_cvt_f32_u32_e32 v2, v3
	v_sub_u32_e32 v5, 0, v3
	v_rcp_iflag_f32_e32 v2, v2
	s_nop 0
	v_mul_f32_e32 v2, 0x4f7ffffe, v2
	v_cvt_u32_f32_e32 v2, v2
	v_mul_lo_u32 v5, v5, v2
	v_mul_hi_u32 v5, v2, v5
	v_add_u32_e32 v2, v2, v5
	s_waitcnt vmcnt(0)
	v_mul_hi_u32 v2, v4, v2
	v_mul_lo_u32 v5, v2, v3
	v_sub_u32_e32 v5, v4, v5
	v_add_u32_e32 v6, 1, v2
	v_cmp_ge_u32_e32 vcc, v5, v3
	v_add_u32_e32 v4, 1, v4
	s_nop 0
	v_cndmask_b32_e32 v2, v2, v6, vcc
	v_sub_u32_e32 v6, v5, v3
	v_cndmask_b32_e32 v5, v5, v6, vcc
	v_add_u32_e32 v6, 1, v2
	v_cmp_ge_u32_e32 vcc, v5, v3
	s_nop 1
	v_cndmask_b32_e32 v2, v2, v6, vcc
	v_mul_lo_u32 v5, v3, v2
	v_add_u32_e32 v3, v5, v3
	v_cmp_ne_u32_e32 vcc, v4, v3
	s_and_saveexec_b64 s[8:9], vcc
	s_xor_b64 s[8:9], exec, s[8:9]
	s_cbranch_execz .LBB0_1466
	s_waitcnt lgkmcnt(0)
	v_mov_b32_e32 v1, 0x3500
	global_load_dword v1, v1, s[70:71] sc1
	s_add_u32 s12, s70, 0x3500
	s_addc_u32 s13, s71, 0
	v_mov_b32_e32 v2, 13
	s_waitcnt vmcnt(0)
	v_cmp_eq_u32_e32 vcc, v1, v2
	s_and_saveexec_b64 s[10:11], vcc
	s_cbranch_execz .LBB0_1465
	s_mov_b32 s3, 1
	s_mov_b64 s[14:15], 0
	v_mov_b32_e32 v1, 0
	s_branch .LBB0_1456

.LBB0_1556:
	s_lshl_b32 s4, s65, 8
	s_add_u32 s4, s70, s4
	s_addc_u32 s5, s71, 0
	v_mov_b32_e32 v2, 0x1000
	v_mov_b32_e32 v4, 1
	global_atomic_add v4, v2, v4, s[4:5] offset:1024 sc0
	v_cvt_f32_u32_e32 v2, v3
	v_sub_u32_e32 v5, 0, v3
	v_rcp_iflag_f32_e32 v2, v2
	s_nop 0
	v_mul_f32_e32 v2, 0x4f7ffffe, v2
	v_cvt_u32_f32_e32 v2, v2
	v_mul_lo_u32 v5, v5, v2
	v_mul_hi_u32 v5, v2, v5
	v_add_u32_e32 v2, v2, v5
	s_waitcnt vmcnt(0)
	v_mul_hi_u32 v2, v4, v2
	v_mul_lo_u32 v5, v2, v3
	v_sub_u32_e32 v5, v4, v5
	v_add_u32_e32 v6, 1, v2
	v_cmp_ge_u32_e32 vcc, v5, v3
	v_add_u32_e32 v4, 1, v4
	s_nop 0
	v_cndmask_b32_e32 v2, v2, v6, vcc
	v_sub_u32_e32 v6, v5, v3
	v_cndmask_b32_e32 v5, v5, v6, vcc
	v_add_u32_e32 v6, 1, v2
	v_cmp_ge_u32_e32 vcc, v5, v3
	s_nop 1
	v_cndmask_b32_e32 v2, v2, v6, vcc
	v_mul_lo_u32 v5, v3, v2
	v_add_u32_e32 v3, v5, v3
	v_cmp_ne_u32_e32 vcc, v4, v3
	s_and_saveexec_b64 s[6:7], vcc
	s_xor_b64 s[6:7], exec, s[6:7]
	s_cbranch_execz .LBB0_1570
	s_waitcnt lgkmcnt(0)
	v_mov_b32_e32 v1, 0x3500
	global_load_dword v1, v1, s[70:71] sc1
	s_add_u32 s10, s70, 0x3500
	s_addc_u32 s11, s71, 0
	v_mov_b32_e32 v2, 14
	s_waitcnt vmcnt(0)
	v_cmp_eq_u32_e32 vcc, v1, v2
	s_and_saveexec_b64 s[8:9], vcc
	s_cbranch_execz .LBB0_1569
	s_mov_b32 s22, 1
	s_mov_b64 s[12:13], 0
	v_mov_b32_e32 v1, 0
	s_branch .LBB0_1560
